# EpiUp (FFN-up epilogue): the 8 serialized SS1 row-stat load round trips replaced by one up-front batch + ds_bpermute gather
# speedup vs baseline: 1.0265x; 1.0038x over previous
; __device__ __forceinline__ float silu_f(float x) { return x * sigm_f(x); }
;     __device__ __forceinline__ void operator()(const pg8::f32x4 (&acc)[2][2][4][2], const Unit& u, int wr, int wc, int fr, int fq) const {
;         const int rbase = u.pm * 256 + wr * 64 + fr, col = u.pn * 128 + wc * 32 + 8 * fq; bf16* HID = (bf16*)(c.ws + WS_HID); const float* SS = (const float*)(c.ws + WS_SS1);
; #pragma unroll
;         for (int ai = 0; ai < 2; ++ai)
; #pragma unroll
;             for (int m = 0; m < 4; ++m) { const int row = rbase + ai * 128 + m * 16; const f32x4* sp = (const f32x4*)(SS + (size_t)row * 16);
;                 const f32x4 a = sp[0], b = sp[1], cc = sp[2], dd = sp[3];
;                 const float tot = ((a[0] + a[1]) + (a[2] + a[3])) + ((b[0] + b[1]) + (b[2] + b[3])) + ((cc[0] + cc[1]) + (cc[2] + cc[3])) + ((dd[0] + dd[1]) + (dd[2] + dd[3]));
;                 const float rstd = 1.f / sqrtf(tot * (1.f / D) + 1e-6f);
;                 f32x4 h0, h1;
; #pragma unroll
;                 for (int j = 0; j < 4; ++j) { h0[j] = silu_f(acc[ai][0][m][0][j] * rstd) * (acc[ai][1][m][0][j] * rstd); h1[j] = silu_f(acc[ai][0][m][1][j] * rstd) * (acc[ai][1][m][1][j] * rstd); }
;                 *(u32x4*)(HID + (size_t)row * DFF + col) = pack8(h0, h1); }
.LBB0_1260:
	v_lshl_add_u32 v144, s4, 8, v146
	v_mbcnt_lo_u32_b32 v214, -1, 0
	v_mbcnt_hi_u32_b32 v214, -1, v214
	v_and_b32_e32 v215, 48, v214
	v_and_b32_e32 v216, 15, v214
	v_lshl_add_u32 v220, v144, 6, v215
	v_lshlrev_b32_e32 v216, 2, v216
	v_add_u32_e32 v221, 0x2000, v220
	global_load_dwordx4 v[178:181], v220, s[18:19]
	global_load_dwordx4 v[182:185], v220, s[18:19] offset:1024
	global_load_dwordx4 v[186:189], v220, s[18:19] offset:2048
	global_load_dwordx4 v[190:193], v220, s[18:19] offset:3072
	global_load_dwordx4 v[194:197], v221, s[18:19]
	global_load_dwordx4 v[198:201], v221, s[18:19] offset:1024
	global_load_dwordx4 v[202:205], v221, s[18:19] offset:2048
	global_load_dwordx4 v[206:209], v221, s[18:19] offset:3072
	v_add_u32_e32 v217, 64, v216
	v_add_u32_e32 v218, 0x80, v216
	v_add_u32_e32 v219, 0xc0, v216
	s_waitcnt vmcnt(7)
	v_add_f32_e32 v178, v178, v179
	v_add_f32_e32 v180, v180, v181
	v_add_f32_e32 v178, v178, v180
	ds_bpermute_b32 v179, v216, v178
	ds_bpermute_b32 v180, v217, v178
	ds_bpermute_b32 v181, v218, v178
	ds_bpermute_b32 v236, v219, v178
	s_waitcnt vmcnt(6)
	v_add_f32_e32 v182, v182, v183
	v_add_f32_e32 v184, v184, v185
	v_add_f32_e32 v182, v182, v184
	ds_bpermute_b32 v183, v216, v182
	ds_bpermute_b32 v184, v217, v182
	ds_bpermute_b32 v185, v218, v182
	ds_bpermute_b32 v237, v219, v182
	s_waitcnt lgkmcnt(4)
	v_add_f32_e32 v228, v179, v180
	v_add_f32_e32 v228, v228, v181
	v_add_f32_e32 v228, v228, v236
	s_waitcnt vmcnt(5)
	v_add_f32_e32 v186, v186, v187
	v_add_f32_e32 v188, v188, v189
	v_add_f32_e32 v186, v186, v188
	ds_bpermute_b32 v187, v216, v186
	ds_bpermute_b32 v188, v217, v186
	ds_bpermute_b32 v189, v218, v186
	ds_bpermute_b32 v238, v219, v186
	s_waitcnt lgkmcnt(4)
	v_add_f32_e32 v229, v183, v184
	v_add_f32_e32 v229, v229, v185
	v_add_f32_e32 v229, v229, v237
	s_waitcnt vmcnt(4)
	v_add_f32_e32 v190, v190, v191
	v_add_f32_e32 v192, v192, v193
	v_add_f32_e32 v190, v190, v192
	ds_bpermute_b32 v191, v216, v190
	ds_bpermute_b32 v192, v217, v190
	ds_bpermute_b32 v193, v218, v190
	ds_bpermute_b32 v239, v219, v190
	s_waitcnt lgkmcnt(4)
	v_add_f32_e32 v230, v187, v188
	v_add_f32_e32 v230, v230, v189
	v_add_f32_e32 v230, v230, v238
	s_waitcnt vmcnt(3)
	v_add_f32_e32 v194, v194, v195
	v_add_f32_e32 v196, v196, v197
	v_add_f32_e32 v194, v194, v196
	ds_bpermute_b32 v195, v216, v194
	ds_bpermute_b32 v196, v217, v194
	ds_bpermute_b32 v197, v218, v194
	ds_bpermute_b32 v240, v219, v194
	s_waitcnt lgkmcnt(4)
	v_add_f32_e32 v231, v191, v192
	v_add_f32_e32 v231, v231, v193
	v_add_f32_e32 v231, v231, v239
	s_waitcnt vmcnt(2)
	v_add_f32_e32 v198, v198, v199
	v_add_f32_e32 v200, v200, v201
	v_add_f32_e32 v198, v198, v200
	ds_bpermute_b32 v199, v216, v198
	ds_bpermute_b32 v200, v217, v198
	ds_bpermute_b32 v201, v218, v198
	ds_bpermute_b32 v241, v219, v198
	s_waitcnt lgkmcnt(4)
	v_add_f32_e32 v232, v195, v196
	v_add_f32_e32 v232, v232, v197
	v_add_f32_e32 v232, v232, v240
	s_waitcnt vmcnt(1)
	v_add_f32_e32 v202, v202, v203
	v_add_f32_e32 v204, v204, v205
	v_add_f32_e32 v202, v202, v204
	ds_bpermute_b32 v203, v216, v202
	ds_bpermute_b32 v204, v217, v202
	ds_bpermute_b32 v205, v218, v202
	ds_bpermute_b32 v242, v219, v202
	s_waitcnt lgkmcnt(4)
	v_add_f32_e32 v233, v199, v200
	v_add_f32_e32 v233, v233, v201
	v_add_f32_e32 v233, v233, v241
	s_waitcnt vmcnt(0)
	v_add_f32_e32 v206, v206, v207
	v_add_f32_e32 v208, v208, v209
	v_add_f32_e32 v206, v206, v208
	ds_bpermute_b32 v207, v216, v206
	ds_bpermute_b32 v208, v217, v206
	ds_bpermute_b32 v209, v218, v206
	ds_bpermute_b32 v243, v219, v206
	s_waitcnt lgkmcnt(4)
	v_add_f32_e32 v234, v203, v204
	v_add_f32_e32 v234, v234, v205
	v_add_f32_e32 v234, v234, v242
	s_waitcnt lgkmcnt(0)
	v_add_f32_e32 v235, v207, v208
	v_add_f32_e32 v235, v235, v209
	v_add_f32_e32 v235, v235, v243
	v_ashrrev_i32_e32 v145, 31, v144
	v_lshlrev_b64 v[154:155], 6, v[144:145]
	v_lshl_add_u64 v[166:167], s[18:19], 0, v[154:155]
	v_mov_b32_e32 v174, v116
	v_mov_b32_e32 v175, v112
	v_mov_b32_e32 v112, v117
	v_mov_b32_e32 v177, v114
	v_mov_b32_e32 v176, v118
	v_mov_b32_e32 v172, v124
	v_mov_b32_e32 v124, v126
	v_lshl_or_b32 v170, s5, 7, v148
	v_mov_b32_e32 v173, v120
	v_mov_b32_e32 v120, v125
	v_mov_b32_e32 v125, v122
	v_mov_b32_e32 v122, v127
	v_ashrrev_i32_e32 v171, 31, v170
	s_nop 0
	s_nop 0
	v_fmamk_f32 v114, v228, 0x3a800000, v152
	v_mul_f32_e32 v116, 0x4f800000, v114
	v_cmp_gt_f32_e32 vcc, s62, v114
	s_nop 1
	v_cndmask_b32_e32 v116, v114, v116, vcc
	v_sqrt_f32_e32 v117, v116
	v_mov_b32_e32 v114, v119
	v_add_u32_e32 v118, -1, v117
	v_add_u32_e32 v119, 1, v117
	v_fma_f32 v126, -v118, v117, v116
	v_fma_f32 v127, -v119, v117, v116
	v_cmp_ge_f32_e64 s[4:5], 0, v126
	s_nop 1
	v_cndmask_b32_e64 v117, v117, v118, s[4:5]
	v_cmp_lt_f32_e64 s[4:5], 0, v127
	s_nop 1
	v_cndmask_b32_e64 v117, v117, v119, s[4:5]
	v_mul_f32_e32 v118, 0x37800000, v117
	v_cndmask_b32_e32 v117, v117, v118, vcc
	v_cmp_class_f32_e32 vcc, v116, v153
	s_nop 1
	v_cndmask_b32_e32 v118, v117, v116, vcc
	v_div_scale_f32 v119, s[4:5], v118, v118, 1.0
	v_rcp_f32_e32 v126, v119
	v_div_scale_f32 v127, vcc, 1.0, v118, 1.0
	v_lshl_add_u64 v[116:117], v[170:171], 1, s[30:31]
	v_fma_f32 v145, -v119, v126, 1.0
	v_fmac_f32_e32 v126, v145, v126
	v_mul_f32_e32 v145, v127, v126
	v_fma_f32 v154, -v119, v145, v127
	v_fmac_f32_e32 v145, v154, v126
	v_fma_f32 v119, -v119, v145, v127
	v_div_fmas_f32 v119, v119, v126, v145
	v_div_fixup_f32 v118, v119, v118, 1.0
	v_pk_mul_f32 v[126:127], v[172:173], v[118:119] op_sel_hi:[1,0]
	v_pk_mul_f32 v[154:155], v[174:175], v[118:119] op_sel_hi:[1,0]
	v_pk_mul_f32 v[120:121], v[120:121], v[118:119] op_sel_hi:[1,0]
; __device__ __forceinline__ float silu_f(float x) { return x * sigm_f(x); }
;     __device__ __forceinline__ void operator()(const pg8::f32x4 (&acc)[2][2][4][2], const Unit& u, int wr, int wc, int fr, int fq) const {
;     ...
;             for (int m = 0; m < 4; ++m) { const int row = rbase + ai * 128 + m * 16; const f32x4* sp = (const f32x4*)(SS + (size_t)row * 16);
;                 const f32x4 a = sp[0], b = sp[1], cc = sp[2], dd = sp[3];
;                 const float tot = ((a[0] + a[1]) + (a[2] + a[3])) + ((b[0] + b[1]) + (b[2] + b[3])) + ((cc[0] + cc[1]) + (cc[2] + cc[3])) + ((dd[0] + dd[1]) + (dd[2] + dd[3]));
;                 const float rstd = 1.f / sqrtf(tot * (1.f / D) + 1e-6f);
;                 f32x4 h0, h1;
; #pragma unroll
;                 for (int j = 0; j < 4; ++j) { h0[j] = silu_f(acc[ai][0][m][0][j] * rstd) * (acc[ai][1][m][0][j] * rstd); h1[j] = silu_f(acc[ai][0][m][1][j] * rstd) * (acc[ai][1][m][1][j] * rstd); }
;                 *(u32x4*)(HID + (size_t)row * DFF + col) = pack8(h0, h1); }
	v_pk_mul_f32 v[112:113], v[112:113], v[118:119] op_sel_hi:[1,0]
	v_pk_mul_f32 v[124:125], v[124:125], v[118:119] op_sel_hi:[1,0]
	v_pk_mul_f32 v[156:157], v[176:177], v[118:119] op_sel_hi:[1,0]
	v_pk_mul_f32 v[122:123], v[122:123], v[118:119] op_sel_hi:[1,0]
	v_pk_mul_f32 v[114:115], v[114:115], v[118:119] op_sel_hi:[1,0]
	v_mul_f32_e32 v118, 0xbfb8aa3b, v127
	v_mul_f32_e32 v119, 0xbfb8aa3b, v155
	v_mul_f32_e32 v145, 0xbfb8aa3b, v121
	v_mul_f32_e32 v158, 0xbfb8aa3b, v113
	v_mul_f32_e32 v159, 0xbfb8aa3b, v125
	v_mul_f32_e32 v161, 0xbfb8aa3b, v123
	v_mul_f32_e32 v162, 0xbfb8aa3b, v115
	v_exp_f32_e32 v118, v118
	v_exp_f32_e32 v119, v119
	v_exp_f32_e32 v145, v145
	v_exp_f32_e32 v158, v158
	v_exp_f32_e32 v159, v159
	v_mul_f32_e32 v160, 0xbfb8aa3b, v157
	v_exp_f32_e32 v161, v161
	v_exp_f32_e32 v162, v162
	v_exp_f32_e32 v160, v160
	v_add_f32_e32 v118, 1.0, v118
	v_add_f32_e32 v119, 1.0, v119
	v_add_f32_e32 v145, 1.0, v145
	v_add_f32_e32 v158, 1.0, v158
	v_add_f32_e32 v159, 1.0, v159
	v_add_f32_e32 v161, 1.0, v161
	v_add_f32_e32 v162, 1.0, v162
	v_rcp_f32_e32 v118, v118
	v_rcp_f32_e32 v119, v119
	v_rcp_f32_e32 v145, v145
	v_rcp_f32_e32 v158, v158
	v_rcp_f32_e32 v159, v159
	v_add_f32_e32 v160, 1.0, v160
	v_rcp_f32_e32 v161, v161
	v_rcp_f32_e32 v162, v162
	v_rcp_f32_e32 v160, v160
	v_mul_f32_e32 v118, v127, v118
	v_mul_f32_e32 v119, v155, v119
	v_mul_f32_e32 v121, v121, v145
	v_mul_f32_e32 v113, v113, v158
	v_mul_f32_e32 v125, v125, v159
	v_mul_f32_e32 v123, v123, v161
	v_mul_f32_e32 v115, v115, v162
	v_mul_f32_e32 v118, v126, v118
	v_mul_f32_e32 v119, v154, v119
	v_mul_f32_e32 v120, v120, v121
	v_mul_f32_e32 v121, v112, v113
	v_mul_f32_e32 v113, v124, v125
	v_mul_f32_e32 v127, v157, v160
	v_mul_f32_e32 v122, v122, v123
	v_mul_f32_e32 v115, v114, v115
	v_cvt_pk_bf16_f32 v112, v118, v120
	v_cvt_pk_bf16_f32 v113, v113, v122
	v_cvt_pk_bf16_f32 v114, v119, v121
	v_mad_i64_i32 v[118:119], s[4:5], v144, s63, v[116:117]
	v_mul_f32_e32 v124, v156, v127
	v_cvt_pk_bf16_f32 v115, v124, v115
	global_store_dwordx4 v[118:119], v[112:115], off
	v_mov_b32_e32 v127, v100
	v_mov_b32_e32 v100, v97
	v_or_b32_e32 v112, 16, v144
	v_ashrrev_i32_e32 v113, 31, v112
	v_lshlrev_b64 v[114:115], 6, v[112:113]
	v_lshl_add_u64 v[114:115], s[18:19], 0, v[114:115]
	v_mov_b32_e32 v114, v108
	v_mov_b32_e32 v115, v104
	v_mov_b32_e32 v104, v109
	v_mov_b32_e32 v97, v106
	v_mov_b32_e32 v126, v96
	v_mov_b32_e32 v96, v110
	s_nop 0
	s_nop 0
	v_fmamk_f32 v106, v229, 0x3a800000, v152
	v_mul_f32_e32 v108, 0x4f800000, v106
	v_cmp_gt_f32_e32 vcc, s62, v106
	v_mov_b32_e32 v109, v102
	s_nop 0
	v_cndmask_b32_e32 v110, v106, v108, vcc
	v_sqrt_f32_e32 v113, v110
	v_mov_b32_e32 v108, v98
	v_mov_b32_e32 v106, v111
	v_add_u32_e32 v98, -1, v113
	v_add_u32_e32 v102, 1, v113
	v_fma_f32 v111, -v98, v113, v110
	v_fma_f32 v118, -v102, v113, v110
	v_cmp_ge_f32_e64 s[4:5], 0, v111
	s_nop 1
	v_cndmask_b32_e64 v98, v113, v98, s[4:5]
	v_cmp_lt_f32_e64 s[4:5], 0, v118
	s_nop 1
	v_cndmask_b32_e64 v98, v98, v102, s[4:5]
	v_mul_f32_e32 v102, 0x37800000, v98
	v_cndmask_b32_e32 v98, v98, v102, vcc
	v_cmp_class_f32_e32 vcc, v110, v153
	v_mov_b32_e32 v102, v99
	s_nop 0
	v_cndmask_b32_e32 v98, v98, v110, vcc
	v_div_scale_f32 v110, s[4:5], v98, v98, 1.0
	v_rcp_f32_e32 v111, v110
	v_div_scale_f32 v99, vcc, 1.0, v98, 1.0
	v_fma_f32 v113, -v110, v111, 1.0
	v_fmac_f32_e32 v111, v113, v111
	v_mul_f32_e32 v113, v99, v111
	v_fma_f32 v118, -v110, v113, v99
	v_fmac_f32_e32 v113, v118, v111
	v_fma_f32 v99, -v110, v113, v99
	v_div_fmas_f32 v99, v99, v111, v113
	v_div_fixup_f32 v98, v99, v98, 1.0
	v_pk_mul_f32 v[96:97], v[96:97], v[98:99] op_sel_hi:[1,0]
	v_pk_mul_f32 v[104:105], v[104:105], v[98:99] op_sel_hi:[1,0]
	v_pk_mul_f32 v[106:107], v[106:107], v[98:99] op_sel_hi:[1,0]
	v_mul_f32_e32 v119, 0xbfb8aa3b, v97
	v_pk_mul_f32 v[110:111], v[114:115], v[98:99] op_sel_hi:[1,0]
	v_pk_mul_f32 v[114:115], v[126:127], v[98:99] op_sel_hi:[1,0]
	v_pk_mul_f32 v[100:101], v[100:101], v[98:99] op_sel_hi:[1,0]
	v_pk_mul_f32 v[108:109], v[108:109], v[98:99] op_sel_hi:[1,0]
	v_pk_mul_f32 v[98:99], v[102:103], v[98:99] op_sel_hi:[1,0]
	v_mul_f32_e32 v113, 0xbfb8aa3b, v105
	v_mul_f32_e32 v121, 0xbfb8aa3b, v107
	v_exp_f32_e32 v119, v119
	v_mul_f32_e32 v118, 0xbfb8aa3b, v101
	v_mul_f32_e32 v120, 0xbfb8aa3b, v109
	v_mul_f32_e32 v122, 0xbfb8aa3b, v99
	v_exp_f32_e32 v113, v113
	v_exp_f32_e32 v121, v121
	v_mul_f32_e32 v102, 0xbfb8aa3b, v111
	v_mul_f32_e32 v103, 0xbfb8aa3b, v115
	v_exp_f32_e32 v118, v118
	v_exp_f32_e32 v120, v120
	v_exp_f32_e32 v122, v122
	v_exp_f32_e32 v102, v102
	v_exp_f32_e32 v103, v103
	v_add_f32_e32 v119, 1.0, v119
	v_add_f32_e32 v113, 1.0, v113
	v_add_f32_e32 v121, 1.0, v121
	v_rcp_f32_e32 v119, v119
	v_add_f32_e32 v118, 1.0, v118
	v_add_f32_e32 v120, 1.0, v120
	v_add_f32_e32 v122, 1.0, v122
	v_rcp_f32_e32 v113, v113
	v_rcp_f32_e32 v121, v121
	v_add_f32_e32 v102, 1.0, v102
	v_add_f32_e32 v103, 1.0, v103
	v_rcp_f32_e32 v118, v118
	v_rcp_f32_e32 v120, v120
	v_rcp_f32_e32 v122, v122
	v_rcp_f32_e32 v102, v102
	v_rcp_f32_e32 v103, v103
	v_mul_f32_e32 v97, v97, v119
	v_mul_f32_e32 v105, v105, v113
	v_mul_f32_e32 v97, v96, v97
	v_mul_f32_e32 v96, v107, v121
	v_mul_f32_e32 v101, v101, v118
	v_mul_f32_e32 v109, v109, v120
	v_mul_f32_e32 v104, v104, v105
	v_mul_f32_e32 v105, v106, v96
	v_mul_f32_e32 v96, v99, v122
	v_mul_f32_e32 v102, v111, v102
	v_mul_f32_e32 v103, v115, v103
	v_mul_f32_e32 v100, v100, v101
	v_mul_f32_e32 v101, v108, v109
	v_mul_f32_e32 v99, v98, v96
	v_mul_f32_e32 v102, v110, v102
	v_mul_f32_e32 v103, v114, v103
	v_cvt_pk_bf16_f32 v96, v102, v104
	v_cvt_pk_bf16_f32 v97, v97, v105
	v_cvt_pk_bf16_f32 v98, v103, v100
; __device__ __forceinline__ float silu_f(float x) { return x * sigm_f(x); }
;     __device__ __forceinline__ void operator()(const pg8::f32x4 (&acc)[2][2][4][2], const Unit& u, int wr, int wc, int fr, int fq) const {
;     ...
;             for (int m = 0; m < 4; ++m) { const int row = rbase + ai * 128 + m * 16; const f32x4* sp = (const f32x4*)(SS + (size_t)row * 16);
;                 const f32x4 a = sp[0], b = sp[1], cc = sp[2], dd = sp[3];
;                 const float tot = ((a[0] + a[1]) + (a[2] + a[3])) + ((b[0] + b[1]) + (b[2] + b[3])) + ((cc[0] + cc[1]) + (cc[2] + cc[3])) + ((dd[0] + dd[1]) + (dd[2] + dd[3]));
;                 const float rstd = 1.f / sqrtf(tot * (1.f / D) + 1e-6f);
;                 f32x4 h0, h1;
; #pragma unroll
;                 for (int j = 0; j < 4; ++j) { h0[j] = silu_f(acc[ai][0][m][0][j] * rstd) * (acc[ai][1][m][0][j] * rstd); h1[j] = silu_f(acc[ai][0][m][1][j] * rstd) * (acc[ai][1][m][1][j] * rstd); }
;                 *(u32x4*)(HID + (size_t)row * DFF + col) = pack8(h0, h1); }
	v_cvt_pk_bf16_f32 v99, v101, v99
	v_mad_i64_i32 v[100:101], s[4:5], v112, s63, v[116:117]
	global_store_dwordx4 v[100:101], v[96:99], off
	v_mov_b32_e32 v114, v92
	v_mov_b32_e32 v115, v88
	v_or_b32_e32 v96, 32, v144
	v_ashrrev_i32_e32 v97, 31, v96
	v_lshlrev_b64 v[98:99], 6, v[96:97]
	v_lshl_add_u64 v[110:111], s[18:19], 0, v[98:99]
	v_mov_b32_e32 v88, v93
	v_mov_b32_e32 v119, v84
	v_mov_b32_e32 v84, v81
	v_mov_b32_e32 v81, v90
	v_mov_b32_e32 v118, v80
	v_mov_b32_e32 v80, v94
	s_nop 0
	s_nop 0
	v_fmamk_f32 v90, v230, 0x3a800000, v152
	v_mul_f32_e32 v92, 0x4f800000, v90
	v_cmp_gt_f32_e32 vcc, s62, v90
	v_mov_b32_e32 v93, v86
	s_nop 0
	v_cndmask_b32_e32 v94, v90, v92, vcc
	v_sqrt_f32_e32 v97, v94
	v_mov_b32_e32 v92, v82
	v_mov_b32_e32 v90, v95
	v_add_u32_e32 v82, -1, v97
	v_add_u32_e32 v86, 1, v97
	v_fma_f32 v95, -v82, v97, v94
	v_fma_f32 v98, -v86, v97, v94
	v_cmp_ge_f32_e64 s[4:5], 0, v95
	s_nop 1
	v_cndmask_b32_e64 v82, v97, v82, s[4:5]
	v_cmp_lt_f32_e64 s[4:5], 0, v98
	s_nop 1
	v_cndmask_b32_e64 v82, v82, v86, s[4:5]
	v_mul_f32_e32 v86, 0x37800000, v82
	v_cndmask_b32_e32 v82, v82, v86, vcc
	v_cmp_class_f32_e32 vcc, v94, v153
	v_mov_b32_e32 v86, v83
	s_nop 0
	v_cndmask_b32_e32 v82, v82, v94, vcc
	v_div_scale_f32 v94, s[4:5], v82, v82, 1.0
	v_rcp_f32_e32 v95, v94
	v_div_scale_f32 v83, vcc, 1.0, v82, 1.0
	v_fma_f32 v97, -v94, v95, 1.0
	v_fmac_f32_e32 v95, v97, v95
	v_mul_f32_e32 v97, v83, v95
	v_fma_f32 v98, -v94, v97, v83
	v_fmac_f32_e32 v97, v98, v95
	v_fma_f32 v83, -v94, v97, v83
	v_div_fmas_f32 v83, v83, v95, v97
	v_div_fixup_f32 v82, v83, v82, 1.0
	v_pk_mul_f32 v[80:81], v[80:81], v[82:83] op_sel_hi:[1,0]
	v_pk_mul_f32 v[84:85], v[84:85], v[82:83] op_sel_hi:[1,0]
	v_mul_f32_e32 v101, 0xbfb8aa3b, v81
	v_mul_f32_e32 v100, 0xbfb8aa3b, v85
	v_exp_f32_e32 v101, v101
	v_exp_f32_e32 v100, v100
	v_pk_mul_f32 v[90:91], v[90:91], v[82:83] op_sel_hi:[1,0]
	v_pk_mul_f32 v[94:95], v[114:115], v[82:83] op_sel_hi:[1,0]
	v_add_f32_e32 v101, 1.0, v101
	v_pk_mul_f32 v[98:99], v[118:119], v[82:83] op_sel_hi:[1,0]
	v_pk_mul_f32 v[88:89], v[88:89], v[82:83] op_sel_hi:[1,0]
	v_pk_mul_f32 v[92:93], v[92:93], v[82:83] op_sel_hi:[1,0]
	v_pk_mul_f32 v[82:83], v[86:87], v[82:83] op_sel_hi:[1,0]
	v_mul_f32_e32 v103, 0xbfb8aa3b, v91
	v_add_f32_e32 v100, 1.0, v100
	v_rcp_f32_e32 v101, v101
	v_mul_f32_e32 v86, 0xbfb8aa3b, v95
	v_mul_f32_e32 v87, 0xbfb8aa3b, v99
	v_mul_f32_e32 v97, 0xbfb8aa3b, v89
	v_mul_f32_e32 v104, 0xbfb8aa3b, v83
	v_exp_f32_e32 v103, v103
	v_rcp_f32_e32 v100, v100
	v_mul_f32_e32 v102, 0xbfb8aa3b, v93
	v_exp_f32_e32 v86, v86
	v_exp_f32_e32 v87, v87
	v_exp_f32_e32 v97, v97
	v_exp_f32_e32 v104, v104
	v_exp_f32_e32 v102, v102
	v_mul_f32_e32 v81, v81, v101
	v_mul_f32_e32 v85, v85, v100
	v_mul_f32_e32 v81, v80, v81
	v_add_f32_e32 v80, 1.0, v103
	v_add_f32_e32 v86, 1.0, v86
	v_add_f32_e32 v87, 1.0, v87
	v_add_f32_e32 v97, 1.0, v97
	v_mul_f32_e32 v84, v84, v85
	v_rcp_f32_e32 v80, v80
	v_add_f32_e32 v85, 1.0, v104
	v_add_f32_e32 v102, 1.0, v102
	v_rcp_f32_e32 v86, v86
	v_rcp_f32_e32 v87, v87
	v_rcp_f32_e32 v97, v97
	v_rcp_f32_e32 v85, v85
	v_rcp_f32_e32 v102, v102
	v_mul_f32_e32 v80, v91, v80
	v_mul_f32_e32 v86, v95, v86
	v_mul_f32_e32 v87, v99, v87
	v_mul_f32_e32 v89, v89, v97
	v_mul_f32_e32 v90, v90, v80
	v_mul_f32_e32 v80, v83, v85
	v_mul_f32_e32 v93, v93, v102
	v_mul_f32_e32 v86, v94, v86
	v_mul_f32_e32 v87, v98, v87
	v_mul_f32_e32 v88, v88, v89
	v_mul_f32_e32 v83, v82, v80
	v_cvt_pk_bf16_f32 v80, v86, v88
	v_cvt_pk_bf16_f32 v81, v81, v90
	v_cvt_pk_bf16_f32 v82, v87, v84
	v_mad_i64_i32 v[84:85], s[4:5], v96, s63, v[116:117]
	v_mul_f32_e32 v89, v92, v93
	v_cvt_pk_bf16_f32 v83, v89, v83
	global_store_dwordx4 v[84:85], v[80:83], off
	v_mov_b32_e32 v98, v72
	v_mov_b32_e32 v99, v76
	v_or_b32_e32 v80, 48, v144
	v_ashrrev_i32_e32 v81, 31, v80
	v_lshlrev_b64 v[82:83], 6, v[80:81]
	v_lshl_add_u64 v[94:95], s[18:19], 0, v[82:83]
	v_mov_b32_e32 v76, v73
	v_mov_b32_e32 v101, v68
	v_mov_b32_e32 v68, v65
	v_mov_b32_e32 v100, v64
	v_mov_b32_e32 v64, v74
	s_nop 0
	s_nop 0
	v_fmamk_f32 v65, v231, 0x3a800000, v152
	v_mul_f32_e32 v72, 0x4f800000, v65
	v_cmp_gt_f32_e32 vcc, s62, v65
	v_mov_b32_e32 v73, v70
	s_nop 0
	v_cndmask_b32_e32 v74, v65, v72, vcc
	v_sqrt_f32_e32 v81, v74
	v_mov_b32_e32 v72, v66
	v_mov_b32_e32 v65, v78
	v_add_u32_e32 v66, -1, v81
	v_add_u32_e32 v70, 1, v81
	v_fma_f32 v78, -v66, v81, v74
	v_fma_f32 v82, -v70, v81, v74
	v_cmp_ge_f32_e64 s[4:5], 0, v78
	v_mov_b32_e32 v78, v75
	s_nop 0
	v_cndmask_b32_e64 v66, v81, v66, s[4:5]
	v_cmp_lt_f32_e64 s[4:5], 0, v82
	s_nop 1
	v_cndmask_b32_e64 v66, v66, v70, s[4:5]
	v_mul_f32_e32 v70, 0x37800000, v66
	v_cndmask_b32_e32 v66, v66, v70, vcc
	v_cmp_class_f32_e32 vcc, v74, v153
	s_nop 1
	v_cndmask_b32_e32 v66, v66, v74, vcc
	v_div_scale_f32 v70, s[4:5], v66, v66, 1.0
	v_rcp_f32_e32 v74, v70
	v_div_scale_f32 v75, vcc, 1.0, v66, 1.0
	v_fma_f32 v81, -v70, v74, 1.0
	v_fmac_f32_e32 v74, v81, v74
	v_mul_f32_e32 v81, v75, v74
	v_fma_f32 v82, -v70, v81, v75
	v_fmac_f32_e32 v81, v82, v74
	v_fma_f32 v70, -v70, v81, v75
	v_div_fmas_f32 v70, v70, v74, v81
	v_div_fixup_f32 v66, v70, v66, 1.0
	v_pk_mul_f32 v[74:75], v[98:99], v[66:67] op_sel_hi:[1,0]
	v_pk_mul_f32 v[68:69], v[68:69], v[66:67] op_sel_hi:[1,0]
	v_pk_mul_f32 v[64:65], v[64:65], v[66:67] op_sel_hi:[1,0]
	v_mul_f32_e32 v70, 0xbfb8aa3b, v75
	v_mul_f32_e32 v85, 0xbfb8aa3b, v69
	v_mul_f32_e32 v86, 0xbfb8aa3b, v65
	v_exp_f32_e32 v70, v70
	v_exp_f32_e32 v85, v85
	v_exp_f32_e32 v86, v86
	v_pk_mul_f32 v[82:83], v[100:101], v[66:67] op_sel_hi:[1,0]
	v_add_f32_e32 v70, 1.0, v70
	v_add_f32_e32 v85, 1.0, v85
	v_add_f32_e32 v86, 1.0, v86
	v_rcp_f32_e32 v70, v70
; __device__ __forceinline__ float silu_f(float x) { return x * sigm_f(x); }
;     __device__ __forceinline__ void operator()(const pg8::f32x4 (&acc)[2][2][4][2], const Unit& u, int wr, int wc, int fr, int fq) const {
;         const int rbase = u.pm * 256 + wr * 64 + fr, col = u.pn * 128 + wc * 32 + 8 * fq; bf16* HID = (bf16*)(c.ws + WS_HID); const float* SS = (const float*)(c.ws + WS_SS1);
; #pragma unroll
;         for (int ai = 0; ai < 2; ++ai)
; #pragma unroll
;             for (int m = 0; m < 4; ++m) { const int row = rbase + ai * 128 + m * 16; const f32x4* sp = (const f32x4*)(SS + (size_t)row * 16);
;                 const f32x4 a = sp[0], b = sp[1], cc = sp[2], dd = sp[3];
;                 const float tot = ((a[0] + a[1]) + (a[2] + a[3])) + ((b[0] + b[1]) + (b[2] + b[3])) + ((cc[0] + cc[1]) + (cc[2] + cc[3])) + ((dd[0] + dd[1]) + (dd[2] + dd[3]));
;                 const float rstd = 1.f / sqrtf(tot * (1.f / D) + 1e-6f);
;                 f32x4 h0, h1;
; #pragma unroll
;                 for (int j = 0; j < 4; ++j) { h0[j] = silu_f(acc[ai][0][m][0][j] * rstd) * (acc[ai][1][m][0][j] * rstd); h1[j] = silu_f(acc[ai][0][m][1][j] * rstd) * (acc[ai][1][m][1][j] * rstd); }
;                 *(u32x4*)(HID + (size_t)row * DFF + col) = pack8(h0, h1); }
	v_rcp_f32_e32 v85, v85
	v_rcp_f32_e32 v86, v86
	v_pk_mul_f32 v[76:77], v[76:77], v[66:67] op_sel_hi:[1,0]
	v_mul_f32_e32 v70, v75, v70
	v_mul_f32_e32 v69, v69, v85
	v_mul_f32_e32 v65, v65, v86
	v_mul_f32_e32 v74, v74, v70
	v_mov_b32_e32 v70, v67
	v_pk_mul_f32 v[72:73], v[72:73], v[66:67] op_sel_hi:[1,0]
	v_pk_mul_f32 v[78:79], v[78:79], v[66:67] op_sel_hi:[1,0]
	v_mul_f32_e32 v68, v68, v69
	v_mul_f32_e32 v69, v64, v65
	v_pk_mul_f32 v[64:65], v[70:71], v[66:67] op_sel_hi:[1,0]
	v_mul_f32_e32 v81, 0xbfb8aa3b, v83
	v_mul_f32_e32 v84, 0xbfb8aa3b, v77
	v_mul_f32_e32 v87, 0xbfb8aa3b, v73
	v_mul_f32_e32 v88, 0xbfb8aa3b, v79
	v_mul_f32_e32 v66, 0xbfb8aa3b, v65
	v_exp_f32_e32 v81, v81
	v_exp_f32_e32 v84, v84
	v_exp_f32_e32 v87, v87
	v_exp_f32_e32 v88, v88
	v_exp_f32_e32 v66, v66
	v_add_f32_e32 v81, 1.0, v81
	v_add_f32_e32 v84, 1.0, v84
	v_add_f32_e32 v87, 1.0, v87
	v_add_f32_e32 v70, 1.0, v88
	v_add_f32_e32 v66, 1.0, v66
	v_rcp_f32_e32 v81, v81
	v_rcp_f32_e32 v84, v84
	v_rcp_f32_e32 v87, v87
	v_rcp_f32_e32 v70, v70
	v_rcp_f32_e32 v66, v66
	v_mul_f32_e32 v75, v83, v81
	v_mul_f32_e32 v77, v77, v84
	v_mul_f32_e32 v67, v73, v87
	v_mul_f32_e32 v70, v79, v70
	v_mul_f32_e32 v65, v65, v66
	v_mul_f32_e32 v75, v82, v75
	v_mul_f32_e32 v76, v76, v77
	v_mul_f32_e32 v67, v72, v67
	v_mul_f32_e32 v70, v78, v70
	v_mul_f32_e32 v71, v64, v65
	v_cvt_pk_bf16_f32 v64, v74, v76
	v_cvt_pk_bf16_f32 v65, v69, v70
	v_cvt_pk_bf16_f32 v66, v75, v68
	v_mad_i64_i32 v[68:69], s[4:5], v80, s63, v[116:117]
	v_cvt_pk_bf16_f32 v67, v67, v71
	global_store_dwordx4 v[68:69], v[64:67], off
	v_mov_b32_e32 v82, v52
	v_mov_b32_e32 v83, v60
	v_add_u32_e32 v64, 0x80, v144
	v_ashrrev_i32_e32 v65, 31, v64
	v_lshlrev_b64 v[66:67], 6, v[64:65]
	v_lshl_add_u64 v[78:79], s[18:19], 0, v[66:67]
	v_mov_b32_e32 v84, v48
	v_mov_b32_e32 v85, v56
	v_mov_b32_e32 v60, v53
	v_mov_b32_e32 v56, v49
	v_mov_b32_e32 v52, v50
	s_nop 0
	v_fmamk_f32 v48, v232, 0x3a800000, v152
	v_mul_f32_e32 v49, 0x4f800000, v48
	v_cmp_gt_f32_e32 vcc, s62, v48
	s_nop 1
	v_cndmask_b32_e32 v53, v48, v49, vcc
	v_sqrt_f32_e32 v65, v53
	v_mov_b32_e32 v48, v54
	v_mov_b32_e32 v49, v62
	v_add_u32_e32 v50, -1, v65
	v_add_u32_e32 v54, 1, v65
	v_fma_f32 v62, -v50, v65, v53
	v_fma_f32 v66, -v54, v65, v53
	v_cmp_ge_f32_e64 s[4:5], 0, v62
	s_nop 1
	v_cndmask_b32_e64 v50, v65, v50, s[4:5]
	v_cmp_lt_f32_e64 s[4:5], 0, v66
	s_nop 1
	v_cndmask_b32_e64 v50, v50, v54, s[4:5]
	v_mul_f32_e32 v54, 0x37800000, v50
	v_cndmask_b32_e32 v50, v50, v54, vcc
	v_cmp_class_f32_e32 vcc, v53, v153
	s_nop 1
	v_cndmask_b32_e32 v50, v50, v53, vcc
	v_div_scale_f32 v54, s[4:5], v50, v50, 1.0
	v_rcp_f32_e32 v62, v54
	v_mov_b32_e32 v53, v58
	v_div_scale_f32 v58, vcc, 1.0, v50, 1.0
	v_fma_f32 v65, -v54, v62, 1.0
	v_fmac_f32_e32 v62, v65, v62
	v_mul_f32_e32 v65, v58, v62
	v_fma_f32 v66, -v54, v65, v58
	v_fmac_f32_e32 v65, v66, v62
	v_fma_f32 v54, -v54, v65, v58
	v_div_fmas_f32 v54, v54, v62, v65
	v_div_fixup_f32 v50, v54, v50, 1.0
	v_pk_mul_f32 v[68:69], v[84:85], v[50:51] op_sel_hi:[1,0]
	v_pk_mul_f32 v[60:61], v[60:61], v[50:51] op_sel_hi:[1,0]
	v_pk_mul_f32 v[56:57], v[56:57], v[50:51] op_sel_hi:[1,0]
	v_pk_mul_f32 v[48:49], v[48:49], v[50:51] op_sel_hi:[1,0]
	v_mul_f32_e32 v58, 0xbfb8aa3b, v69
	v_mul_f32_e32 v62, 0xbfb8aa3b, v61
	v_mul_f32_e32 v65, 0xbfb8aa3b, v57
	v_mul_f32_e32 v70, 0xbfb8aa3b, v49
	v_exp_f32_e32 v58, v58
	v_exp_f32_e32 v62, v62
	v_exp_f32_e32 v65, v65
	v_exp_f32_e32 v70, v70
	v_add_f32_e32 v58, 1.0, v58
	v_add_f32_e32 v62, 1.0, v62
	v_add_f32_e32 v65, 1.0, v65
	v_add_f32_e32 v70, 1.0, v70
	v_rcp_f32_e32 v58, v58
	v_rcp_f32_e32 v62, v62
	v_rcp_f32_e32 v65, v65
	v_rcp_f32_e32 v70, v70
	v_mul_f32_e32 v58, v69, v58
	v_mul_f32_e32 v61, v61, v62
	v_mul_f32_e32 v57, v57, v65
	v_mul_f32_e32 v49, v49, v70
	v_mov_b32_e32 v62, v55
	v_mul_f32_e32 v65, v68, v58
	v_mul_f32_e32 v56, v56, v57
	v_mul_f32_e32 v57, v48, v49
	v_pk_mul_f32 v[48:49], v[62:63], v[50:51] op_sel_hi:[1,0]
	v_mov_b32_e32 v58, v51
	v_pk_mul_f32 v[66:67], v[82:83], v[50:51] op_sel_hi:[1,0]
	v_pk_mul_f32 v[52:53], v[52:53], v[50:51] op_sel_hi:[1,0]
	v_mul_f32_e32 v55, 0xbfb8aa3b, v49
	v_pk_mul_f32 v[50:51], v[58:59], v[50:51] op_sel_hi:[1,0]
	v_mul_f32_e32 v71, 0xbfb8aa3b, v53
	v_exp_f32_e32 v55, v55
	v_mul_f32_e32 v58, 0xbfb8aa3b, v51
	v_mul_f32_e32 v54, 0xbfb8aa3b, v67
	v_exp_f32_e32 v71, v71
	v_exp_f32_e32 v58, v58
	v_exp_f32_e32 v54, v54
	v_add_f32_e32 v55, 1.0, v55
	v_add_f32_e32 v71, 1.0, v71
	v_rcp_f32_e32 v55, v55
	v_add_f32_e32 v58, 1.0, v58
	v_add_f32_e32 v54, 1.0, v54
	v_mul_f32_e32 v60, v60, v61
	v_rcp_f32_e32 v61, v71
	v_rcp_f32_e32 v58, v58
	v_rcp_f32_e32 v54, v54
	v_mul_f32_e32 v49, v49, v55
	v_mul_f32_e32 v53, v53, v61
	v_mul_f32_e32 v49, v48, v49
	v_mul_f32_e32 v48, v51, v58
	v_mul_f32_e32 v54, v67, v54
	v_mul_f32_e32 v52, v52, v53
	v_mul_f32_e32 v51, v50, v48
	v_mul_f32_e32 v54, v66, v54
	v_cvt_pk_bf16_f32 v48, v54, v60
	v_cvt_pk_bf16_f32 v49, v57, v49
	v_cvt_pk_bf16_f32 v50, v65, v56
	v_cvt_pk_bf16_f32 v51, v52, v51
	v_mad_i64_i32 v[52:53], s[4:5], v64, s63, v[116:117]
	global_store_dwordx4 v[52:53], v[48:51], off
	v_mov_b32_e32 v66, v36
	v_mov_b32_e32 v67, v44
	v_add_u32_e32 v48, 0x90, v144
	v_ashrrev_i32_e32 v49, 31, v48
	v_lshlrev_b64 v[50:51], 6, v[48:49]
	v_lshl_add_u64 v[62:63], s[18:19], 0, v[50:51]
	v_mov_b32_e32 v68, v32
	v_mov_b32_e32 v69, v40
	v_mov_b32_e32 v44, v37
	v_mov_b32_e32 v40, v33
	v_mov_b32_e32 v36, v34
	s_nop 0
	v_fmamk_f32 v32, v233, 0x3a800000, v152
	v_mul_f32_e32 v33, 0x4f800000, v32
	v_cmp_gt_f32_e32 vcc, s62, v32
	s_nop 1
	v_cndmask_b32_e32 v37, v32, v33, vcc
	v_sqrt_f32_e32 v49, v37
	v_mov_b32_e32 v32, v38
	v_mov_b32_e32 v33, v46
	v_add_u32_e32 v34, -1, v49
; __device__ __forceinline__ float silu_f(float x) { return x * sigm_f(x); }
;     __device__ __forceinline__ void operator()(const pg8::f32x4 (&acc)[2][2][4][2], const Unit& u, int wr, int wc, int fr, int fq) const {
;         const int rbase = u.pm * 256 + wr * 64 + fr, col = u.pn * 128 + wc * 32 + 8 * fq; bf16* HID = (bf16*)(c.ws + WS_HID); const float* SS = (const float*)(c.ws + WS_SS1);
; #pragma unroll
;         for (int ai = 0; ai < 2; ++ai)
; #pragma unroll
;             for (int m = 0; m < 4; ++m) { const int row = rbase + ai * 128 + m * 16; const f32x4* sp = (const f32x4*)(SS + (size_t)row * 16);
;                 const f32x4 a = sp[0], b = sp[1], cc = sp[2], dd = sp[3];
;                 const float tot = ((a[0] + a[1]) + (a[2] + a[3])) + ((b[0] + b[1]) + (b[2] + b[3])) + ((cc[0] + cc[1]) + (cc[2] + cc[3])) + ((dd[0] + dd[1]) + (dd[2] + dd[3]));
;                 const float rstd = 1.f / sqrtf(tot * (1.f / D) + 1e-6f);
;                 f32x4 h0, h1;
; #pragma unroll
;                 for (int j = 0; j < 4; ++j) { h0[j] = silu_f(acc[ai][0][m][0][j] * rstd) * (acc[ai][1][m][0][j] * rstd); h1[j] = silu_f(acc[ai][0][m][1][j] * rstd) * (acc[ai][1][m][1][j] * rstd); }
;                 *(u32x4*)(HID + (size_t)row * DFF + col) = pack8(h0, h1); }
	v_add_u32_e32 v38, 1, v49
	v_fma_f32 v46, -v34, v49, v37
	v_fma_f32 v50, -v38, v49, v37
	v_cmp_ge_f32_e64 s[4:5], 0, v46
	s_nop 1
	v_cndmask_b32_e64 v34, v49, v34, s[4:5]
	v_cmp_lt_f32_e64 s[4:5], 0, v50
	s_nop 1
	v_cndmask_b32_e64 v34, v34, v38, s[4:5]
	v_mul_f32_e32 v38, 0x37800000, v34
	v_cndmask_b32_e32 v34, v34, v38, vcc
	v_cmp_class_f32_e32 vcc, v37, v153
	s_nop 1
	v_cndmask_b32_e32 v34, v34, v37, vcc
	v_div_scale_f32 v38, s[4:5], v34, v34, 1.0
	v_rcp_f32_e32 v46, v38
	v_mov_b32_e32 v37, v42
	v_div_scale_f32 v42, vcc, 1.0, v34, 1.0
	v_fma_f32 v49, -v38, v46, 1.0
	v_fmac_f32_e32 v46, v49, v46
	v_mul_f32_e32 v49, v42, v46
	v_fma_f32 v50, -v38, v49, v42
	v_fmac_f32_e32 v49, v50, v46
	v_fma_f32 v38, -v38, v49, v42
	v_div_fmas_f32 v38, v38, v46, v49
	v_div_fixup_f32 v34, v38, v34, 1.0
	v_pk_mul_f32 v[52:53], v[68:69], v[34:35] op_sel_hi:[1,0]
	v_pk_mul_f32 v[40:41], v[40:41], v[34:35] op_sel_hi:[1,0]
	v_mul_f32_e32 v42, 0xbfb8aa3b, v53
	v_mul_f32_e32 v49, 0xbfb8aa3b, v41
	v_exp_f32_e32 v42, v42
	v_exp_f32_e32 v49, v49
	v_pk_mul_f32 v[32:33], v[32:33], v[34:35] op_sel_hi:[1,0]
	v_pk_mul_f32 v[44:45], v[44:45], v[34:35] op_sel_hi:[1,0]
	v_mul_f32_e32 v54, 0xbfb8aa3b, v33
	v_mul_f32_e32 v46, 0xbfb8aa3b, v45
	v_exp_f32_e32 v54, v54
	v_add_f32_e32 v42, 1.0, v42
	v_exp_f32_e32 v46, v46
	v_add_f32_e32 v49, 1.0, v49
	v_rcp_f32_e32 v42, v42
	v_rcp_f32_e32 v49, v49
	v_pk_mul_f32 v[36:37], v[36:37], v[34:35] op_sel_hi:[1,0]
	v_add_f32_e32 v54, 1.0, v54
	v_mul_f32_e32 v55, 0xbfb8aa3b, v37
	v_add_f32_e32 v46, 1.0, v46
	v_rcp_f32_e32 v54, v54
	v_mul_f32_e32 v42, v53, v42
	v_rcp_f32_e32 v46, v46
	v_mul_f32_e32 v41, v41, v49
	v_mul_f32_e32 v49, v52, v42
	v_exp_f32_e32 v42, v55
	v_mul_f32_e32 v33, v33, v54
	v_mul_f32_e32 v45, v45, v46
	v_mul_f32_e32 v40, v40, v41
	v_mul_f32_e32 v41, v32, v33
	v_add_f32_e32 v32, 1.0, v42
	v_mov_b32_e32 v46, v39
	v_mul_f32_e32 v44, v44, v45
	v_rcp_f32_e32 v45, v32
	v_pk_mul_f32 v[32:33], v[46:47], v[34:35] op_sel_hi:[1,0]
	v_mov_b32_e32 v42, v35
	v_pk_mul_f32 v[50:51], v[66:67], v[34:35] op_sel_hi:[1,0]
	v_mul_f32_e32 v39, 0xbfb8aa3b, v33
	v_pk_mul_f32 v[34:35], v[42:43], v[34:35] op_sel_hi:[1,0]
	v_exp_f32_e32 v39, v39
	v_mul_f32_e32 v42, 0xbfb8aa3b, v35
	v_mul_f32_e32 v38, 0xbfb8aa3b, v51
	v_exp_f32_e32 v42, v42
	v_exp_f32_e32 v38, v38
	v_add_f32_e32 v39, 1.0, v39
	v_rcp_f32_e32 v39, v39
	v_add_f32_e32 v42, 1.0, v42
	v_add_f32_e32 v38, 1.0, v38
	v_rcp_f32_e32 v42, v42
	v_rcp_f32_e32 v38, v38
	v_mul_f32_e32 v33, v33, v39
	v_mul_f32_e32 v37, v37, v45
	v_mul_f32_e32 v33, v32, v33
	v_mul_f32_e32 v32, v35, v42
	v_mul_f32_e32 v38, v51, v38
	v_mul_f32_e32 v36, v36, v37
	v_mul_f32_e32 v35, v34, v32
	v_mul_f32_e32 v38, v50, v38
	v_cvt_pk_bf16_f32 v32, v38, v44
	v_cvt_pk_bf16_f32 v33, v41, v33
	v_cvt_pk_bf16_f32 v34, v49, v40
	v_cvt_pk_bf16_f32 v35, v36, v35
	v_mad_i64_i32 v[36:37], s[4:5], v48, s63, v[116:117]
	v_add_u32_e32 v48, 0xa0, v144
	v_ashrrev_i32_e32 v49, 31, v48
	global_store_dwordx4 v[36:37], v[32:35], off
	v_mov_b32_e32 v52, v16
	v_mov_b32_e32 v50, v20
	v_lshlrev_b64 v[32:33], 6, v[48:49]
	v_lshl_add_u64 v[44:45], s[18:19], 0, v[32:33]
	v_mov_b32_e32 v53, v24
	v_mov_b32_e32 v24, v17
	v_mov_b32_e32 v51, v28
	v_mov_b32_e32 v28, v21
	s_nop 0
	s_nop 0
	v_fmamk_f32 v16, v234, 0x3a800000, v152
	v_mul_f32_e32 v20, 0x4f800000, v16
	v_cmp_gt_f32_e32 vcc, s62, v16
	s_nop 1
	v_cndmask_b32_e32 v20, v16, v20, vcc
	v_sqrt_f32_e32 v32, v20
	v_mov_b32_e32 v16, v22
	v_add_u32_e32 v17, -1, v32
	v_add_u32_e32 v21, 1, v32
	v_fma_f32 v22, -v17, v32, v20
	v_fma_f32 v33, -v21, v32, v20
	v_cmp_ge_f32_e64 s[4:5], 0, v22
	s_nop 1
	v_cndmask_b32_e64 v17, v32, v17, s[4:5]
	v_cmp_lt_f32_e64 s[4:5], 0, v33
	s_nop 1
	v_cndmask_b32_e64 v17, v17, v21, s[4:5]
	v_mul_f32_e32 v21, 0x37800000, v17
	v_cndmask_b32_e32 v17, v17, v21, vcc
	v_cmp_class_f32_e32 vcc, v20, v153
	s_nop 1
	v_cndmask_b32_e32 v20, v17, v20, vcc
	v_div_scale_f32 v21, s[4:5], v20, v20, 1.0
	v_rcp_f32_e32 v22, v21
	v_mov_b32_e32 v17, v30
	v_div_scale_f32 v30, vcc, 1.0, v20, 1.0
	v_fma_f32 v32, -v21, v22, 1.0
	v_fmac_f32_e32 v22, v32, v22
	v_mul_f32_e32 v32, v30, v22
	v_fma_f32 v33, -v21, v32, v30
	v_fmac_f32_e32 v32, v33, v22
	v_fma_f32 v21, -v21, v32, v30
	v_div_fmas_f32 v21, v21, v22, v32
	v_div_fixup_f32 v20, v21, v20, 1.0
	v_pk_mul_f32 v[32:33], v[50:51], v[20:21] op_sel_hi:[1,0]
	v_pk_mul_f32 v[28:29], v[28:29], v[20:21] op_sel_hi:[1,0]
	v_pk_mul_f32 v[34:35], v[52:53], v[20:21] op_sel_hi:[1,0]
	v_pk_mul_f32 v[24:25], v[24:25], v[20:21] op_sel_hi:[1,0]
	v_pk_mul_f32 v[16:17], v[16:17], v[20:21] op_sel_hi:[1,0]
	v_mul_f32_e32 v21, 0xbfb8aa3b, v33
	v_mul_f32_e32 v30, 0xbfb8aa3b, v29
	v_exp_f32_e32 v21, v21
	v_exp_f32_e32 v30, v30
	v_mul_f32_e32 v36, 0xbfb8aa3b, v25
	v_mul_f32_e32 v37, 0xbfb8aa3b, v17
	v_add_f32_e32 v21, 1.0, v21
	v_add_f32_e32 v30, 1.0, v30
	v_rcp_f32_e32 v21, v21
	v_rcp_f32_e32 v30, v30
	v_exp_f32_e32 v36, v36
	v_exp_f32_e32 v37, v37
	v_mul_f32_e32 v21, v33, v21
	v_mul_f32_e32 v29, v29, v30
; __device__ __forceinline__ float silu_f(float x) { return x * sigm_f(x); }
;     __device__ __forceinline__ void operator()(const pg8::f32x4 (&acc)[2][2][4][2], const Unit& u, int wr, int wc, int fr, int fq) const {
;         const int rbase = u.pm * 256 + wr * 64 + fr, col = u.pn * 128 + wc * 32 + 8 * fq; bf16* HID = (bf16*)(c.ws + WS_HID); const float* SS = (const float*)(c.ws + WS_SS1);
; #pragma unroll
;         for (int ai = 0; ai < 2; ++ai)
; #pragma unroll
;             for (int m = 0; m < 4; ++m) { const int row = rbase + ai * 128 + m * 16; const f32x4* sp = (const f32x4*)(SS + (size_t)row * 16);
;                 const f32x4 a = sp[0], b = sp[1], cc = sp[2], dd = sp[3];
;                 const float tot = ((a[0] + a[1]) + (a[2] + a[3])) + ((b[0] + b[1]) + (b[2] + b[3])) + ((cc[0] + cc[1]) + (cc[2] + cc[3])) + ((dd[0] + dd[1]) + (dd[2] + dd[3]));
;                 const float rstd = 1.f / sqrtf(tot * (1.f / D) + 1e-6f);
;                 f32x4 h0, h1;
; #pragma unroll
;                 for (int j = 0; j < 4; ++j) { h0[j] = silu_f(acc[ai][0][m][0][j] * rstd) * (acc[ai][1][m][0][j] * rstd); h1[j] = silu_f(acc[ai][0][m][1][j] * rstd) * (acc[ai][1][m][1][j] * rstd); }
;                 *(u32x4*)(HID + (size_t)row * DFF + col) = pack8(h0, h1); }
	v_mul_f32_e32 v21, v32, v21
	v_mul_f32_e32 v32, v28, v29
	v_mov_b32_e32 v28, v18
	v_mov_b32_e32 v29, v26
	v_add_f32_e32 v36, 1.0, v36
	v_add_f32_e32 v37, 1.0, v37
	v_pk_mul_f32 v[28:29], v[28:29], v[20:21] op_sel_hi:[1,0]
	v_rcp_f32_e32 v36, v36
	v_rcp_f32_e32 v30, v37
	v_mul_f32_e32 v18, 0xbfb8aa3b, v29
	v_exp_f32_e32 v18, v18
	v_mul_f32_e32 v25, v25, v36
	v_mul_f32_e32 v17, v17, v30
	v_mul_f32_e32 v24, v24, v25
	v_mul_f32_e32 v25, v16, v17
	v_add_f32_e32 v16, 1.0, v18
	v_mov_b32_e32 v30, v23
	v_rcp_f32_e32 v33, v16
	v_pk_mul_f32 v[16:17], v[30:31], v[20:21] op_sel_hi:[1,0]
	v_mov_b32_e32 v26, v19
	v_mul_f32_e32 v18, 0xbfb8aa3b, v17
	v_exp_f32_e32 v23, v18
	v_pk_mul_f32 v[18:19], v[26:27], v[20:21] op_sel_hi:[1,0]
	v_mul_f32_e32 v22, 0xbfb8aa3b, v35
	v_mul_f32_e32 v20, 0xbfb8aa3b, v19
	v_exp_f32_e32 v20, v20
	v_exp_f32_e32 v22, v22
	v_add_f32_e32 v23, 1.0, v23
	v_rcp_f32_e32 v23, v23
	v_add_f32_e32 v20, 1.0, v20
	v_rcp_f32_e32 v20, v20
	v_add_f32_e32 v22, 1.0, v22
	v_rcp_f32_e32 v22, v22
	v_mul_f32_e32 v17, v17, v23
	v_mul_f32_e32 v17, v16, v17
	v_mul_f32_e32 v16, v19, v20
	v_mul_f32_e32 v19, v18, v16
	v_cvt_pk_bf16_f32 v16, v21, v32
	v_add_u32_e32 v32, 0xb0, v144
	v_mul_f32_e32 v22, v35, v22
	v_mul_f32_e32 v26, v29, v33
	v_cvt_pk_bf16_f32 v17, v25, v17
	v_mad_i64_i32 v[20:21], s[4:5], v48, s63, v[116:117]
	v_ashrrev_i32_e32 v33, 31, v32
	v_mul_f32_e32 v22, v34, v22
	v_mul_f32_e32 v26, v28, v26
	v_cvt_pk_bf16_f32 v18, v22, v24
	v_cvt_pk_bf16_f32 v19, v26, v19
	global_store_dwordx4 v[20:21], v[16:19], off
	v_mov_b32_e32 v36, v0
	v_mov_b32_e32 v34, v4
	v_lshlrev_b64 v[16:17], 6, v[32:33]
	v_lshl_add_u64 v[28:29], s[18:19], 0, v[16:17]
	v_mov_b32_e32 v37, v8
	v_mov_b32_e32 v8, v1
	v_mov_b32_e32 v35, v12
	v_mov_b32_e32 v12, v5
	s_nop 0
	s_nop 0
	v_fmamk_f32 v0, v235, 0x3a800000, v152
	v_mul_f32_e32 v4, 0x4f800000, v0
	v_cmp_gt_f32_e32 vcc, s62, v0
	s_nop 1
	v_cndmask_b32_e32 v4, v0, v4, vcc
	v_sqrt_f32_e32 v16, v4
	v_mov_b32_e32 v0, v6
	v_add_u32_e32 v1, -1, v16
	v_add_u32_e32 v5, 1, v16
	v_fma_f32 v6, -v1, v16, v4
	v_fma_f32 v17, -v5, v16, v4
	v_cmp_ge_f32_e64 s[4:5], 0, v6
	s_nop 1
	v_cndmask_b32_e64 v1, v16, v1, s[4:5]
	v_cmp_lt_f32_e64 s[4:5], 0, v17
	s_nop 1
	v_cndmask_b32_e64 v1, v1, v5, s[4:5]
	v_mul_f32_e32 v5, 0x37800000, v1
	v_cndmask_b32_e32 v1, v1, v5, vcc
	v_cmp_class_f32_e32 vcc, v4, v153
	s_nop 1
	v_cndmask_b32_e32 v4, v1, v4, vcc
	v_div_scale_f32 v5, s[4:5], v4, v4, 1.0
	v_rcp_f32_e32 v6, v5
	v_mov_b32_e32 v1, v14
	v_div_scale_f32 v14, vcc, 1.0, v4, 1.0
	v_fma_f32 v16, -v5, v6, 1.0
	v_fmac_f32_e32 v6, v16, v6
	v_mul_f32_e32 v16, v14, v6
	v_fma_f32 v17, -v5, v16, v14
	v_fmac_f32_e32 v16, v17, v6
	v_fma_f32 v5, -v5, v16, v14
	v_div_fmas_f32 v5, v5, v6, v16
	v_div_fixup_f32 v4, v5, v4, 1.0
	v_pk_mul_f32 v[16:17], v[34:35], v[4:5] op_sel_hi:[1,0]
	v_pk_mul_f32 v[18:19], v[36:37], v[4:5] op_sel_hi:[1,0]
	v_pk_mul_f32 v[12:13], v[12:13], v[4:5] op_sel_hi:[1,0]
	v_pk_mul_f32 v[8:9], v[8:9], v[4:5] op_sel_hi:[1,0]
	v_pk_mul_f32 v[0:1], v[0:1], v[4:5] op_sel_hi:[1,0]
	v_mul_f32_e32 v5, 0xbfb8aa3b, v17
	v_exp_f32_e32 v5, v5
	v_mul_f32_e32 v14, 0xbfb8aa3b, v13
	v_exp_f32_e32 v14, v14
	v_mul_f32_e32 v21, 0xbfb8aa3b, v1
	v_add_f32_e32 v5, 1.0, v5
	v_rcp_f32_e32 v5, v5
	v_add_f32_e32 v14, 1.0, v14
	v_rcp_f32_e32 v14, v14
	v_mul_f32_e32 v20, 0xbfb8aa3b, v9
	v_mul_f32_e32 v5, v17, v5
	v_mul_f32_e32 v5, v16, v5
	v_exp_f32_e32 v16, v21
	v_exp_f32_e32 v20, v20
	v_mul_f32_e32 v13, v13, v14
	v_mul_f32_e32 v17, v12, v13
	v_add_f32_e32 v12, 1.0, v16
	v_rcp_f32_e32 v14, v12
	v_mov_b32_e32 v12, v2
	v_mov_b32_e32 v13, v10
	v_add_f32_e32 v20, 1.0, v20
	v_pk_mul_f32 v[12:13], v[12:13], v[4:5] op_sel_hi:[1,0]
	v_rcp_f32_e32 v20, v20
	v_mul_f32_e32 v2, 0xbfb8aa3b, v13
	v_exp_f32_e32 v2, v2
	v_mul_f32_e32 v1, v1, v14
	v_mul_f32_e32 v9, v9, v20
	v_mul_f32_e32 v8, v8, v9
	v_mul_f32_e32 v9, v0, v1
	v_add_f32_e32 v0, 1.0, v2
	v_mov_b32_e32 v14, v7
	v_rcp_f32_e32 v16, v0
	v_pk_mul_f32 v[0:1], v[14:15], v[4:5] op_sel_hi:[1,0]
	v_mov_b32_e32 v10, v3
	v_mul_f32_e32 v2, 0xbfb8aa3b, v1
	v_exp_f32_e32 v7, v2
	v_pk_mul_f32 v[2:3], v[10:11], v[4:5] op_sel_hi:[1,0]
	v_mul_f32_e32 v6, 0xbfb8aa3b, v19
	v_mul_f32_e32 v4, 0xbfb8aa3b, v3
	v_exp_f32_e32 v4, v4
	v_exp_f32_e32 v6, v6
	v_add_f32_e32 v7, 1.0, v7
	v_rcp_f32_e32 v7, v7
	v_add_f32_e32 v4, 1.0, v4
	v_add_f32_e32 v6, 1.0, v6
	v_rcp_f32_e32 v4, v4
	v_rcp_f32_e32 v6, v6
	v_mul_f32_e32 v1, v1, v7
	v_mul_f32_e32 v1, v0, v1
	v_mul_f32_e32 v0, v3, v4
	v_mul_f32_e32 v6, v19, v6
	v_mul_f32_e32 v10, v13, v16
	v_mul_f32_e32 v3, v2, v0
	v_cvt_pk_bf16_f32 v0, v5, v17
	v_mad_i64_i32 v[4:5], s[4:5], v32, s63, v[116:117]
	s_andn2_b64 vcc, exec, s[2:3]
	s_mov_b64 s[2:3], -1
	v_mul_f32_e32 v6, v18, v6
	v_mul_f32_e32 v10, v12, v10
	v_cvt_pk_bf16_f32 v1, v9, v1
	v_cvt_pk_bf16_f32 v2, v6, v8
	v_cvt_pk_bf16_f32 v3, v10, v3
	global_store_dwordx4 v[4:5], v[0:3], off
	s_cbranch_vccnz .LBB0_1253
	s_andn2_b64 vcc, exec, s[10:11]
	s_cbranch_vccnz .LBB0_1252
	s_barrier
	s_branch .LBB0_1252
